# PLE projection GEMM tiles run in the ff1 phase tail (one tile per block, same code path) instead of at the end of the ff2 phase
# speedup vs baseline: 1.0017x; 1.0017x over previous
; #define PG8_BAR __builtin_amdgcn_s_barrier()
; template <class Epi, bool SEQ>
; DEV void gemm_phase(PG8_LAS unsigned char* lds, const Gemm g, const Epi& E) {
;   const int tid = tidx(), wid = __builtin_amdgcn_readfirstlane(tid >> 6), lane = tid & 63, wr = wid >> 2, wc = wid & 3, fr = lane & 15, fq = lane >> 4;
;   const int G = gridDim.x - g.cskip, cblk = bidx() - g.cskip;
;   if (cblk < 0) return;
;   const int nt = g.K / BK;
;   unsigned voffA[2], voffB[2];
; #pragma unroll
;   for (int i = 0; i < 2; ++i) { int R, C; stage_rc(tid * 16 + i * 8192, R, C); const int Rb = Epi::PERM ? ((R & ~31) + perm32(R & 31)) : R;
;     voffA[i] = (unsigned)(R * g.lda + C) * 2u; voffB[i] = (unsigned)(Rb * g.ldb + C) * 2u; }
;   const size_t kstep = (size_t)(BK * 2);
;   const size_t hstepA = (size_t)HALF * g.lda * 2, hstepB = (size_t)HALF * g.ldb * 2;
;   const size_t tstepA = 2 * hstepA, tstepB = 2 * hstepB;
;   const unsigned ldsw = (unsigned)wid * 1024u;
;   const int aoff = lds_byte(wr * 64 + fr, fq * 8), boff = lds_byte(wc * 32 + fr, fq * 8);
;     ...
;   Unit cur, nxt; int ui = 0;
;   if (!next_unit<SEQ>(g, 0, G, cblk, cur)) return;
;   f32x4 acc[2][2][4][2];
; #pragma unroll
;   for (int a = 0; a < 2; ++a)
; #pragma unroll
;     for (int b = 0; b < 2; ++b)
; #pragma unroll
;       for (int m = 0; m < 4; ++m)
; #pragma unroll
;         for (int n = 0; n < 2; ++n) acc[a][b][m][n] = (f32x4){0.f, 0.f, 0.f, 0.f};
;   bf16x8 At[4][2], B0[2][2], B1[2][2];
;   const char* cA = PG8_ABASE(cur); const char* cB = PG8_BBASE(cur);
;   PG8_STAGE(PG8_SB(0, 0), cB, voffB); PG8_STAGE(PG8_SB(0, 1), cB + hstepB, voffB); PG8_STAGE(PG8_SA(0, 0), cA, voffA); PG8_STAGE(PG8_SA(0, 1), cA + hstepA, voffA);
;   if (wr == 1) PG8_BAR;
;   PG8_WAIT_V(2); PG8_BAR;
;   PG8_STAGE(PG8_SB(1, 0), cB + kstep, voffB); PG8_STAGE(PG8_SA(1, 0), cA + kstep, voffA); PG8_STAGE(PG8_SB(1, 1), cB + hstepB + kstep, voffB);
; DEV void run_phase(const Params& pin, int ph, unsigned char* smem) {
;     ...
;       for (int part = 0; part < 2; ++part) {
;         const pg8::Gemm g{part ? (const bf16_t*)(p.ws + WS_Z + ZO_PB) : (const bf16_t*)(p.ws + WS_Z + ZO_HID), part ? WT + WT_PP : WT + WT_FF2,
;                           part ? DPLE : DFF, part ? DPLE : DFF, part ? DPLE : DFF / 2, part ? TP / 256 : MTOK / 256, D / 256, 0, part ? 0 : DFF / 2, 0,
;                           (size_t)(part ? 0 : DFF / 2), part ? 32 : 0, part ? 1 : 2};
.LBB0_156:
	v_readlane_b32 s4, v248, 45
	s_nop 1
	s_cmp_eq_u32 s4, 7
	s_cbranch_scc1 .Lp7_ret
	s_branch .LBB0_177
.LBB0_157:
	v_readlane_b32 s4, v250, 16
	v_mov_b32_e32 v18, v171
	v_readlane_b32 s5, v250, 17
	s_load_dword s3, s[4:5], 0x10
	s_and_b64 s[4:5], s[0:1], exec
	s_mov_b32 s13, 0
	v_readlane_b32 s16, v248, 37
	s_mov_b32 s6, s74
	v_readlane_b32 s98, v248, 45
	s_nop 1
	s_cmp_eq_u32 s98, 7
	s_cselect_b32 s98, 0, 0
	s_sub_i32 s6, s6, s98
	s_waitcnt lgkmcnt(0)
	s_lshr_b32 s3, s3, 16
	s_cmp_lg_u32 s3, 0
	s_cselect_b64 s[4:5], -1, 0
	s_cmp_lg_u64 s[4:5], 0
	v_readlane_b32 s18, v248, 39
	s_addc_u32 s42, s18, 0
	s_movk_i32 s99, 0xc0
	s_cmp_lg_u32 s98, 0
	s_cselect_b32 s42, s99, s42
	s_add_i32 s43, s6, s13
	s_cmp_lt_i32 s43, 0
	v_readfirstlane_b32 s12, v18
	v_readlane_b32 s17, v248, 38
	v_readlane_b32 s19, v248, 40
	s_cbranch_scc1 .LBB0_156
	s_and_b64 s[4:5], s[0:1], exec
	s_cselect_b32 s44, 0x44, 64
	s_lshl_b32 s3, s44, 2
	s_xor_b32 s45, s2, 1
	s_lshl_b32 s46, s3, s45
	s_and_b64 s[4:5], s[0:1], exec
	s_cselect_b32 s46, 0x200, s46
	s_cmp_ge_u32 s43, s46
	s_cbranch_scc1 .LBB0_156
	v_lshlrev_b32_e32 v0, 4, v18
	v_add_u32_e32 v1, 0x2000, v0
	v_ashrrev_i32_e32 v2, 31, v1
	v_lshrrev_b32_e32 v2, 22, v2
	v_add_u32_e32 v2, v1, v2
	v_ashrrev_i32_e32 v2, 10, v2
	s_ashr_i32 s15, s12, 8
	v_mul_i32_i24_e32 v3, 0x400, v2
	s_and_b64 s[2:3], s[0:1], exec
	v_sub_u32_e32 v1, v1, v3
	s_mov_b32 s2, 0x100000
	v_lshrrev_b32_e32 v3, 4, v1
	s_cselect_b32 s6, s2, 0x10000
	s_ashr_i32 s14, s12, 6
	v_bitop3_b32 v1, v3, v1, 32 bitop3:0x6c
	s_lshl_b32 s47, s14, 10
	v_ashrrev_i32_e32 v3, 31, v1
	s_and_b64 s[2:3], s[0:1], exec
	v_lshrrev_b32_e32 v3, 26, v3
	s_mov_b32 s2, 0x1a80000
	v_add_u32_e32 v3, v1, v3
	s_cselect_b32 s2, s2, 0x2480000
	v_ashrrev_i32_e32 v4, 6, v3
	v_and_b32_e32 v3, 0xc0, v3
	s_cselect_b32 s48, 0x1000, 0
	s_cselect_b32 s49, s31, s41
	s_cselect_b32 s50, s30, s40
	s_add_u32 s51, s28, s2
	v_sub_u32_e32 v1, v1, v3
	s_addc_u32 s52, s29, 0
	v_ashrrev_i16_sdwa v1, v200, sext(v1) dst_sel:DWORD dst_unused:UNUSED_PAD src0_sel:DWORD src1_sel:BYTE_0
	v_lshlrev_b32_e32 v5, 3, v2
	s_and_b64 s[2:3], s[0:1], exec
	v_bfe_i32 v14, v1, 0, 16
	v_bfe_i32 v1, v18, 27, 1
	v_and_b32_e32 v5, 0x7ffffff0, v5
	s_cselect_b32 s2, 12, 8
	v_lshlrev_b32_e32 v2, 5, v2
	v_lshrrev_b32_e32 v1, 22, v1
	v_add_lshl_u32 v12, v4, v5, s2
	v_and_b32_e32 v13, 32, v2
	v_add_u32_e32 v1, v0, v1
	v_or_b32_e32 v2, v12, v13
	v_and_b32_e32 v1, 0xfffffc00, v1
	v_add_lshl_u32 v128, v2, v14, 1
	v_sub_u32_e32 v0, v0, v1
	v_ashrrev_i32_e32 v2, 31, v18
	v_lshrrev_b32_e32 v1, 4, v0
	v_lshrrev_b32_e32 v2, 26, v2
	v_bitop3_b32 v1, v1, v0, 32 bitop3:0x6c
	v_ashrrev_i32_e32 v0, 31, v0
	v_add_u32_e32 v2, v18, v2
	v_lshrrev_b32_e32 v0, 26, v0
	v_ashrrev_i32_e32 v2, 6, v2
	v_add_u32_e32 v0, v1, v0
	v_lshlrev_b32_e32 v3, 3, v2
	v_ashrrev_i32_e32 v0, 6, v0
	v_and_b32_e32 v3, 0x7ffffff0, v3
	v_add_lshl_u32 v15, v0, v3, s2
	s_lshr_b32 s3, s43, 4
	s_mul_i32 s3, s3, s45
	s_add_i32 s2, s43, s3
	s_mov_b32 s59, 0
	s_lshr_b32 s53, s44, 1
	s_bfe_u32 s3, s2, 0xd0003
	s_and_b32 s2, s2, 7
	s_mul_i32 s2, s53, s2
	s_add_i32 s2, s2, s3
	s_lshr_b32 s3, s2, 2
	s_and_b32 s5, s3, 0xffc
	s_sub_i32 s3, s44, s5
	s_min_i32 s8, s3, 4
	v_mul_i32_i24_e32 v0, 64, v0
	s_and_b32 s9, s2, 15
	s_sext_i32_i8 s2, s8
	v_sub_u32_e32 v0, v1, v0
	v_cvt_f32_i32_e32 v1, s2
	v_lshlrev_b32_e32 v2, 5, v2
	v_and_b32_e32 v16, 32, v2
	v_ashrrev_i16_sdwa v0, v200, sext(v0) dst_sel:DWORD dst_unused:UNUSED_PAD src0_sel:DWORD src1_sel:BYTE_0
	v_or_b32_e32 v2, v15, v16
	v_bfe_i32 v17, v0, 0, 16
	v_add_lshl_u32 v168, v2, v17, 1
	v_rcp_iflag_f32_e32 v2, v1
	v_cvt_f32_ubyte0_e32 v0, s9
	s_ashr_i32 s3, s2, 30
	s_or_b32 s4, s3, 1
	v_mul_f32_e32 v2, v0, v2
	v_trunc_f32_e32 v2, v2
	v_fma_f32 v0, -v2, v1, v0
	v_cvt_i32_f32_e32 v2, v2
	v_cmp_ge_f32_e64 s[2:3], |v0|, |v1|
	s_and_b64 s[2:3], s[2:3], exec
	s_cselect_b32 s2, s4, 0
	v_readfirstlane_b32 s3, v2
	s_add_i32 s2, s3, s2
	s_sext_i32_i8 s4, s2
	s_mul_i32 s2, s2, s8
	s_sub_i32 s2, s9, s2
	s_and_b32 s2, s2, 0xff
	s_add_i32 s8, s5, s2
	s_cmp_eq_u32 s59, 1
	s_cselect_b64 s[2:3], -1, 0
	s_cmp_lg_u32 s59, 0
	s_cselect_b64 s[16:17], -1, 0
	s_and_b64 s[2:3], s[16:17], s[2:3]
	s_and_b32 s18, s43, 15
	s_lshl_b32 s18, s18, 9
	s_mul_i32 s18, s18, s45
	s_and_b64 s[2:3], s[0:1], exec
	s_mov_b32 s9, s7
	s_cselect_b32 s54, 21, 17
	s_lshl_b64 s[2:3], s[8:9], s54
	s_mov_b32 s9, s18
	s_mov_b32 s5, 0
	s_add_u32 s9, s51, s9
	s_addc_u32 s19, s52, s5
	s_ashr_i32 s5, s4, 31
	s_lshl_b64 s[16:17], s[4:5], s54
	s_add_u32 s36, s9, s16
	s_addc_u32 s37, s19, s17
	s_add_i32 s9, s47, 0
	s_add_i32 m0, s9, 0x10000
	v_mov_b32_e32 v129, v169
	global_load_lds_dwordx4 v168, s[36:37]
	s_add_i32 m0, s9, 0x12000
	s_add_u32 s5, s50, s18
	s_addc_u32 s18, s49, 0
	s_add_u32 s16, s36, s6
	global_load_lds_dwordx4 v128, s[36:37]
	s_addc_u32 s17, s37, 0
	s_add_i32 m0, s9, 0x14000
	v_lshl_add_u64 v[0:1], s[36:37], 0, v[168:169]
	global_load_lds_dwordx4 v168, s[16:17]
	s_add_i32 m0, s9, 0x16000
	s_add_u32 s26, s5, s2
	s_addc_u32 s27, s18, s3
	s_add_i32 s55, s9, 0x2000
	global_load_lds_dwordx4 v128, s[16:17]
	s_mov_b32 m0, s9
	s_add_u32 s2, s26, s6
	global_load_lds_dwordx4 v168, s[26:27]
	s_mov_b32 m0, s55
	s_addc_u32 s3, s27, 0
	s_add_i32 s56, s9, 0x4000
	global_load_lds_dwordx4 v128, s[26:27]
	s_mov_b32 m0, s56
	s_add_i32 s57, s9, 0x6000
	global_load_lds_dwordx4 v168, s[2:3]
	s_mov_b32 m0, s57
	s_cmp_eq_u32 s15, 1
	global_load_lds_dwordx4 v128, s[2:3]
	v_lshl_add_u64 v[2:3], s[36:37], 0, v[128:129]
	v_lshl_add_u64 v[4:5], s[16:17], 0, v[168:169]
	v_lshl_add_u64 v[6:7], s[16:17], 0, v[128:129]
	v_lshl_add_u64 v[8:9], s[26:27], 0, v[168:169]
	v_lshl_add_u64 v[10:11], s[26:27], 0, v[128:129]
	s_cselect_b64 s[2:3], -1, 0
	s_cmp_lg_u32 s15, 1
	s_cbranch_scc1 .LBB0_161
	s_barrier

; DEV void run_phase(const Params& pin, int ph, unsigned char* smem) {
;     ...
;       for (int part = 0; part < 2; ++part) {
;         const pg8::Gemm g{part ? (const bf16_t*)(p.ws + WS_Z + ZO_PB) : (const bf16_t*)(p.ws + WS_Z + ZO_HID), part ? WT + WT_PP : WT + WT_FF2,
;                           part ? DPLE : DFF, part ? DPLE : DFF, part ? DPLE : DFF / 2, part ? TP / 256 : MTOK / 256, D / 256, 0, part ? 0 : DFF / 2, 0,
;                           (size_t)(part ? 0 : DFF / 2), part ? 32 : 0, part ? 1 : 2};
;         const pg8::EpiSplit2 E{(bf16_t*)(p.ws + WS_Z + (part ? ZO_PROJ : ZO_F)), H};
;         pg8::gemm_phase<pg8::EpiSplit2, false>(lds, g, E);
.LBB0_212:
	s_add_u32 s40, s28, 0x11300000
	s_addc_u32 s41, s29, 0
	s_mov_b64 s[0:1], 0
	s_mov_b32 s2, 1
	s_branch .LBB0_157
